# GEMM K-loop: all s_setprio flips deleted (A/B of the per-phase flips)
# speedup vs baseline: 1.0058x; 1.0058x over previous
.LBB0_64:
	s_add_i32 s33, s42, 2
	s_add_u32 s46, s40, 0x80
	s_addc_u32 s43, s41, 0
	s_add_i32 s80, 0, 0x10000
	s_cmp_eq_u32 s84, s42
	s_cselect_b32 s43, s1, s43
	s_cselect_b32 s42, s0, s46
	s_cselect_b32 s47, s75, vcc_hi
	s_cselect_b32 s46, s74, vcc_lo
	s_add_i32 s5, 0, 0x14000
	v_add_u32_e32 v140, s80, v185
	v_add_u32_e32 v166, s5, v185
	ds_read_b128 v[128:131], v140
	ds_read_b128 v[132:135], v140 offset:1024
	ds_read_b128 v[136:139], v140 offset:2048
	ds_read_b128 v[140:143], v140 offset:3072
	ds_read_b128 v[144:147], v166
	ds_read_b128 v[148:151], v166 offset:1024
	ds_read_b128 v[152:155], v166 offset:2048
	ds_read_b128 v[166:169], v166 offset:3072
	v_lshl_add_u64 v[182:183], s[40:41], 0, v[162:163]
	s_add_i32 m0, s28, 0xc000
	ds_read_b128 v[170:173], v188
	ds_read_b128 v[174:177], v188 offset:1024
	ds_read_b128 v[178:181], v188 offset:2048
	ds_read_b128 v[214:217], v188 offset:3072
	ds_read_b128 v[218:221], v188 offset:4096
	ds_read_b128 v[222:225], v188 offset:5120
	ds_read_b128 v[226:229], v188 offset:6144
	ds_read_b128 v[230:233], v188 offset:7168
	global_load_lds_dwordx4 v[182:183], off
	v_lshl_add_u64 v[182:183], s[40:41], 0, v[164:165]
	s_add_i32 m0, s28, 0xe000
	s_nop 0
	global_load_lds_dwordx4 v[182:183], off
	s_waitcnt vmcnt(8)
	s_waitcnt lgkmcnt(0)
	s_barrier
	s_waitcnt lgkmcnt(0)
	v_mfma_f32_16x16x32_bf16 v[124:127], v[128:131], v[170:173], v[124:127]
	v_mfma_f32_16x16x32_bf16 v[120:123], v[136:139], v[170:173], v[120:123]
	v_mfma_f32_16x16x32_bf16 v[108:111], v[128:131], v[178:181], v[108:111]
	v_mfma_f32_16x16x32_bf16 v[104:107], v[136:139], v[178:181], v[104:107]
	v_mfma_f32_16x16x32_bf16 v[92:95], v[128:131], v[218:221], v[92:95]
	v_mfma_f32_16x16x32_bf16 v[88:91], v[136:139], v[218:221], v[88:91]
	v_mfma_f32_16x16x32_bf16 v[76:79], v[128:131], v[226:229], v[76:79]
	v_mfma_f32_16x16x32_bf16 v[72:75], v[136:139], v[226:229], v[72:75]
	v_mfma_f32_16x16x32_bf16 v[124:127], v[132:135], v[174:177], v[124:127]
	v_mfma_f32_16x16x32_bf16 v[120:123], v[140:143], v[174:177], v[120:123]
	v_mfma_f32_16x16x32_bf16 v[108:111], v[132:135], v[214:217], v[108:111]
	v_mfma_f32_16x16x32_bf16 v[104:107], v[140:143], v[214:217], v[104:107]
	v_mfma_f32_16x16x32_bf16 v[92:95], v[132:135], v[222:225], v[92:95]
	v_mfma_f32_16x16x32_bf16 v[88:91], v[140:143], v[222:225], v[88:91]
	v_mfma_f32_16x16x32_bf16 v[76:79], v[132:135], v[230:233], v[76:79]
	v_mfma_f32_16x16x32_bf16 v[72:75], v[140:143], v[230:233], v[72:75]
	v_mfma_f32_16x16x32_bf16 v[116:119], v[144:147], v[170:173], v[116:119]
	v_mfma_f32_16x16x32_bf16 v[112:115], v[152:155], v[170:173], v[112:115]
	v_mfma_f32_16x16x32_bf16 v[100:103], v[144:147], v[178:181], v[100:103]
	v_mfma_f32_16x16x32_bf16 v[96:99], v[152:155], v[178:181], v[96:99]
	v_mfma_f32_16x16x32_bf16 v[84:87], v[144:147], v[218:221], v[84:87]
	v_mfma_f32_16x16x32_bf16 v[80:83], v[152:155], v[218:221], v[80:83]
	v_mfma_f32_16x16x32_bf16 v[68:71], v[144:147], v[226:229], v[68:71]
	v_mfma_f32_16x16x32_bf16 v[64:67], v[152:155], v[226:229], v[64:67]
	v_mfma_f32_16x16x32_bf16 v[116:119], v[148:151], v[174:177], v[116:119]
	v_mfma_f32_16x16x32_bf16 v[112:115], v[166:169], v[174:177], v[112:115]
	v_mfma_f32_16x16x32_bf16 v[100:103], v[148:151], v[214:217], v[100:103]
	v_mfma_f32_16x16x32_bf16 v[96:99], v[166:169], v[214:217], v[96:99]
	v_mfma_f32_16x16x32_bf16 v[84:87], v[148:151], v[222:225], v[84:87]
	v_mfma_f32_16x16x32_bf16 v[80:83], v[166:169], v[222:225], v[80:83]
	v_mfma_f32_16x16x32_bf16 v[68:71], v[148:151], v[230:233], v[68:71]
	v_mfma_f32_16x16x32_bf16 v[64:67], v[166:169], v[230:233], v[64:67]
	s_barrier
	s_add_i32 s80, s80, s27
	v_lshl_add_u64 v[182:183], s[46:47], 0, v[192:193]
	s_mov_b32 m0, s80
	ds_read_b128 v[170:173], v188 offset:16384
	ds_read_b128 v[174:177], v188 offset:17408
	ds_read_b128 v[178:181], v188 offset:18432
	ds_read_b128 v[214:217], v188 offset:19456
	ds_read_b128 v[218:221], v188 offset:20480
	ds_read_b128 v[222:225], v188 offset:21504
	ds_read_b128 v[226:229], v188 offset:22528
	ds_read_b128 v[230:233], v188 offset:23552
	global_load_lds_dwordx4 v[182:183], off
	s_add_i32 m0, s80, 0x2000
	v_lshl_add_u64 v[190:191], s[46:47], 0, v[160:161]
	s_add_u32 s46, s46, s30
	s_addc_u32 s47, s47, 0
	s_add_i32 s5, s5, s27
	global_load_lds_dwordx4 v[190:191], off
	v_lshl_add_u64 v[200:201], s[46:47], 0, v[192:193]
	s_mov_b32 m0, s5
	v_lshl_add_u64 v[234:235], s[46:47], 0, v[160:161]
	global_load_lds_dwordx4 v[200:201], off
	s_add_i32 m0, s5, 0x2000
	v_lshl_add_u64 v[236:237], s[42:43], 0, v[156:157]
	global_load_lds_dwordx4 v[234:235], off
	s_mov_b32 m0, s28
	v_lshl_add_u64 v[238:239], s[42:43], 0, v[158:159]
	global_load_lds_dwordx4 v[236:237], off
	s_mov_b32 m0, s69
	s_nop 0
	global_load_lds_dwordx4 v[238:239], off
	s_waitcnt vmcnt(8)
	s_waitcnt lgkmcnt(0)
	s_barrier
	s_waitcnt lgkmcnt(0)
	v_mfma_f32_16x16x32_bf16 v[60:63], v[128:131], v[170:173], v[60:63]
	v_mfma_f32_16x16x32_bf16 v[56:59], v[136:139], v[170:173], v[56:59]
	v_mfma_f32_16x16x32_bf16 v[44:47], v[128:131], v[178:181], v[44:47]
	v_mfma_f32_16x16x32_bf16 v[40:43], v[136:139], v[178:181], v[40:43]
	v_mfma_f32_16x16x32_bf16 v[28:31], v[128:131], v[218:221], v[28:31]
	v_mfma_f32_16x16x32_bf16 v[24:27], v[136:139], v[218:221], v[24:27]
	v_mfma_f32_16x16x32_bf16 v[12:15], v[128:131], v[226:229], v[12:15]
	v_mfma_f32_16x16x32_bf16 v[8:11], v[136:139], v[226:229], v[8:11]
	v_mfma_f32_16x16x32_bf16 v[60:63], v[132:135], v[174:177], v[60:63]
	v_mfma_f32_16x16x32_bf16 v[56:59], v[140:143], v[174:177], v[56:59]
	v_mfma_f32_16x16x32_bf16 v[44:47], v[132:135], v[214:217], v[44:47]
	v_mfma_f32_16x16x32_bf16 v[40:43], v[140:143], v[214:217], v[40:43]
	v_mfma_f32_16x16x32_bf16 v[28:31], v[132:135], v[222:225], v[28:31]
	v_mfma_f32_16x16x32_bf16 v[24:27], v[140:143], v[222:225], v[24:27]
	v_mfma_f32_16x16x32_bf16 v[12:15], v[132:135], v[230:233], v[12:15]
	v_mfma_f32_16x16x32_bf16 v[8:11], v[140:143], v[230:233], v[8:11]
	v_mfma_f32_16x16x32_bf16 v[52:55], v[144:147], v[170:173], v[52:55]
	v_mfma_f32_16x16x32_bf16 v[48:51], v[152:155], v[170:173], v[48:51]
	v_mfma_f32_16x16x32_bf16 v[36:39], v[144:147], v[178:181], v[36:39]
	v_mfma_f32_16x16x32_bf16 v[32:35], v[152:155], v[178:181], v[32:35]
	v_mfma_f32_16x16x32_bf16 v[20:23], v[144:147], v[218:221], v[20:23]
	v_mfma_f32_16x16x32_bf16 v[16:19], v[152:155], v[218:221], v[16:19]
	v_mfma_f32_16x16x32_bf16 v[4:7], v[144:147], v[226:229], v[4:7]
	v_mfma_f32_16x16x32_bf16 v[0:3], v[152:155], v[226:229], v[0:3]
	v_mfma_f32_16x16x32_bf16 v[52:55], v[148:151], v[174:177], v[52:55]
	v_mfma_f32_16x16x32_bf16 v[48:51], v[166:169], v[174:177], v[48:51]
	v_mfma_f32_16x16x32_bf16 v[36:39], v[148:151], v[214:217], v[36:39]
	v_mfma_f32_16x16x32_bf16 v[32:35], v[166:169], v[214:217], v[32:35]
	v_mfma_f32_16x16x32_bf16 v[20:23], v[148:151], v[222:225], v[20:23]
	v_mfma_f32_16x16x32_bf16 v[16:19], v[166:169], v[222:225], v[16:19]
	v_mfma_f32_16x16x32_bf16 v[4:7], v[148:151], v[230:233], v[4:7]
	v_mfma_f32_16x16x32_bf16 v[0:3], v[166:169], v[230:233], v[0:3]
	s_barrier
.Lmy_sp3:
	s_add_i32 s5, 0, 0x18000
	s_add_i32 s46, 0, 0x1c000
	v_add_u32_e32 v140, s5, v185
	v_add_u32_e32 v166, s46, v185
	ds_read_b128 v[128:131], v140
	ds_read_b128 v[132:135], v140 offset:1024
	ds_read_b128 v[136:139], v140 offset:2048
	ds_read_b128 v[140:143], v140 offset:3072
	ds_read_b128 v[144:147], v166
	ds_read_b128 v[148:151], v166 offset:1024
	ds_read_b128 v[152:155], v166 offset:2048
	ds_read_b128 v[166:169], v166 offset:3072
	s_add_u32 s42, s42, s30
	s_addc_u32 s43, s43, 0
	s_mov_b32 m0, s72
	v_lshl_add_u64 v[240:241], s[42:43], 0, v[156:157]
	ds_read_b128 v[170:173], v188 offset:32768
	ds_read_b128 v[174:177], v188 offset:33792
	ds_read_b128 v[178:181], v188 offset:34816
	ds_read_b128 v[214:217], v188 offset:35840
	ds_read_b128 v[218:221], v188 offset:36864
	ds_read_b128 v[222:225], v188 offset:37888
	ds_read_b128 v[226:229], v188 offset:38912
	ds_read_b128 v[230:233], v188 offset:39936
	global_load_lds_dwordx4 v[240:241], off
	v_lshl_add_u64 v[240:241], s[42:43], 0, v[158:159]
	s_mov_b32 m0, s76
	s_nop 0
	global_load_lds_dwordx4 v[240:241], off
	s_waitcnt vmcnt(8)
	s_waitcnt lgkmcnt(0)
	s_barrier
	s_waitcnt lgkmcnt(0)
	v_mfma_f32_16x16x32_bf16 v[124:127], v[128:131], v[170:173], v[124:127]
	v_mfma_f32_16x16x32_bf16 v[120:123], v[136:139], v[170:173], v[120:123]
	v_mfma_f32_16x16x32_bf16 v[108:111], v[128:131], v[178:181], v[108:111]
	v_mfma_f32_16x16x32_bf16 v[104:107], v[136:139], v[178:181], v[104:107]
	v_mfma_f32_16x16x32_bf16 v[92:95], v[128:131], v[218:221], v[92:95]
	v_mfma_f32_16x16x32_bf16 v[88:91], v[136:139], v[218:221], v[88:91]
	v_mfma_f32_16x16x32_bf16 v[76:79], v[128:131], v[226:229], v[76:79]
	v_mfma_f32_16x16x32_bf16 v[72:75], v[136:139], v[226:229], v[72:75]
	v_mfma_f32_16x16x32_bf16 v[124:127], v[132:135], v[174:177], v[124:127]
	v_mfma_f32_16x16x32_bf16 v[120:123], v[140:143], v[174:177], v[120:123]
	v_mfma_f32_16x16x32_bf16 v[108:111], v[132:135], v[214:217], v[108:111]
	v_mfma_f32_16x16x32_bf16 v[104:107], v[140:143], v[214:217], v[104:107]
	v_mfma_f32_16x16x32_bf16 v[92:95], v[132:135], v[222:225], v[92:95]
	v_mfma_f32_16x16x32_bf16 v[88:91], v[140:143], v[222:225], v[88:91]
	v_mfma_f32_16x16x32_bf16 v[76:79], v[132:135], v[230:233], v[76:79]
	v_mfma_f32_16x16x32_bf16 v[72:75], v[140:143], v[230:233], v[72:75]
	v_mfma_f32_16x16x32_bf16 v[116:119], v[144:147], v[170:173], v[116:119]
	v_mfma_f32_16x16x32_bf16 v[112:115], v[152:155], v[170:173], v[112:115]
	v_mfma_f32_16x16x32_bf16 v[100:103], v[144:147], v[178:181], v[100:103]
	v_mfma_f32_16x16x32_bf16 v[96:99], v[152:155], v[178:181], v[96:99]
	v_mfma_f32_16x16x32_bf16 v[84:87], v[144:147], v[218:221], v[84:87]
	v_mfma_f32_16x16x32_bf16 v[80:83], v[152:155], v[218:221], v[80:83]
	v_mfma_f32_16x16x32_bf16 v[68:71], v[144:147], v[226:229], v[68:71]
	v_mfma_f32_16x16x32_bf16 v[64:67], v[152:155], v[226:229], v[64:67]
	v_mfma_f32_16x16x32_bf16 v[116:119], v[148:151], v[174:177], v[116:119]
	v_mfma_f32_16x16x32_bf16 v[112:115], v[166:169], v[174:177], v[112:115]
	v_mfma_f32_16x16x32_bf16 v[100:103], v[148:151], v[214:217], v[100:103]
	v_mfma_f32_16x16x32_bf16 v[96:99], v[166:169], v[214:217], v[96:99]
	v_mfma_f32_16x16x32_bf16 v[84:87], v[148:151], v[222:225], v[84:87]
	v_mfma_f32_16x16x32_bf16 v[80:83], v[166:169], v[222:225], v[80:83]
	v_mfma_f32_16x16x32_bf16 v[68:71], v[148:151], v[230:233], v[68:71]
	v_mfma_f32_16x16x32_bf16 v[64:67], v[166:169], v[230:233], v[64:67]
	s_barrier
	s_add_i32 s5, s5, s27
	v_lshl_add_u64 v[182:183], v[182:183], 0, s[70:71]
	s_mov_b32 m0, s5
	ds_read_b128 v[170:173], v188 offset:49152
	ds_read_b128 v[174:177], v188 offset:50176
	ds_read_b128 v[178:181], v188 offset:51200
	ds_read_b128 v[214:217], v188 offset:52224
	ds_read_b128 v[218:221], v188 offset:53248
	ds_read_b128 v[222:225], v188 offset:54272
	ds_read_b128 v[226:229], v188 offset:55296
	ds_read_b128 v[230:233], v188 offset:56320
	global_load_lds_dwordx4 v[182:183], off
	v_lshl_add_u64 v[182:183], v[190:191], 0, s[70:71]
	s_add_i32 m0, s5, 0x2000
	s_add_i32 s5, s46, s27
	global_load_lds_dwordx4 v[182:183], off
	v_lshl_add_u64 v[182:183], v[200:201], 0, s[70:71]
	s_mov_b32 m0, s5
	s_nop 0
	global_load_lds_dwordx4 v[182:183], off
	v_lshl_add_u64 v[182:183], v[234:235], 0, s[70:71]
	s_add_i32 m0, s5, 0x2000
	s_nop 0
	global_load_lds_dwordx4 v[182:183], off
	v_lshl_add_u64 v[182:183], v[236:237], 0, s[70:71]
	s_mov_b32 m0, s81
	s_nop 0
	global_load_lds_dwordx4 v[182:183], off
	v_lshl_add_u64 v[182:183], v[238:239], 0, s[70:71]
	s_mov_b32 m0, s82
	s_nop 0
	global_load_lds_dwordx4 v[182:183], off
	s_waitcnt vmcnt(8)
	s_waitcnt lgkmcnt(0)
	s_barrier
	s_waitcnt lgkmcnt(0)
	v_mfma_f32_16x16x32_bf16 v[60:63], v[128:131], v[170:173], v[60:63]
	v_mfma_f32_16x16x32_bf16 v[56:59], v[136:139], v[170:173], v[56:59]
	v_mfma_f32_16x16x32_bf16 v[44:47], v[128:131], v[178:181], v[44:47]
	v_mfma_f32_16x16x32_bf16 v[40:43], v[136:139], v[178:181], v[40:43]
	v_mfma_f32_16x16x32_bf16 v[28:31], v[128:131], v[218:221], v[28:31]
	v_mfma_f32_16x16x32_bf16 v[24:27], v[136:139], v[218:221], v[24:27]
	v_mfma_f32_16x16x32_bf16 v[12:15], v[128:131], v[226:229], v[12:15]
	v_mfma_f32_16x16x32_bf16 v[8:11], v[136:139], v[226:229], v[8:11]
	v_mfma_f32_16x16x32_bf16 v[60:63], v[132:135], v[174:177], v[60:63]
	v_mfma_f32_16x16x32_bf16 v[56:59], v[140:143], v[174:177], v[56:59]
	v_mfma_f32_16x16x32_bf16 v[44:47], v[132:135], v[214:217], v[44:47]
	v_mfma_f32_16x16x32_bf16 v[40:43], v[140:143], v[214:217], v[40:43]
	v_mfma_f32_16x16x32_bf16 v[28:31], v[132:135], v[222:225], v[28:31]
	v_mfma_f32_16x16x32_bf16 v[24:27], v[140:143], v[222:225], v[24:27]
	v_mfma_f32_16x16x32_bf16 v[12:15], v[132:135], v[230:233], v[12:15]
	v_mfma_f32_16x16x32_bf16 v[8:11], v[140:143], v[230:233], v[8:11]
	v_mfma_f32_16x16x32_bf16 v[52:55], v[144:147], v[170:173], v[52:55]
	v_mfma_f32_16x16x32_bf16 v[48:51], v[152:155], v[170:173], v[48:51]
	v_mfma_f32_16x16x32_bf16 v[36:39], v[144:147], v[178:181], v[36:39]
	v_mfma_f32_16x16x32_bf16 v[32:35], v[152:155], v[178:181], v[32:35]
	v_mfma_f32_16x16x32_bf16 v[20:23], v[144:147], v[218:221], v[20:23]
	v_mfma_f32_16x16x32_bf16 v[16:19], v[152:155], v[218:221], v[16:19]
	v_mfma_f32_16x16x32_bf16 v[4:7], v[144:147], v[226:229], v[4:7]
	v_mfma_f32_16x16x32_bf16 v[0:3], v[152:155], v[226:229], v[0:3]
	v_mfma_f32_16x16x32_bf16 v[52:55], v[148:151], v[174:177], v[52:55]
	v_mfma_f32_16x16x32_bf16 v[48:51], v[166:169], v[174:177], v[48:51]
	v_mfma_f32_16x16x32_bf16 v[36:39], v[148:151], v[214:217], v[36:39]
	v_mfma_f32_16x16x32_bf16 v[32:35], v[166:169], v[214:217], v[32:35]
	v_mfma_f32_16x16x32_bf16 v[20:23], v[148:151], v[222:225], v[20:23]
	v_mfma_f32_16x16x32_bf16 v[16:19], v[166:169], v[222:225], v[16:19]
	v_mfma_f32_16x16x32_bf16 v[4:7], v[148:151], v[230:233], v[4:7]
	v_mfma_f32_16x16x32_bf16 v[0:3], v[166:169], v[230:233], v[0:3]
	s_barrier
	s_add_u32 s40, s40, 0x100
	s_addc_u32 s41, s41, 0
	s_add_u32 vcc_lo, vcc_lo, 0x100
	s_addc_u32 vcc_hi, vcc_hi, 0
	s_cmp_ge_u32 s33, s78
	s_mov_b32 s42, s33
	s_cbranch_scc0 .LBB0_64
	s_and_b64 vcc, exec, s[66:67]
	s_cbranch_vccz .LBB0_67
	s_barrier

.Lmy_peel:
	s_add_i32 s33, s42, 2
	s_add_u32 s46, s40, 0x80
	s_addc_u32 s43, s41, 0
	s_add_i32 s80, 0, 0x10000
	s_cmp_eq_u32 s84, s42
	s_cselect_b32 s43, s1, s43
	s_cselect_b32 s42, s0, s46
	s_cselect_b32 s47, s75, vcc_hi
	s_cselect_b32 s46, s74, vcc_lo
	s_add_i32 s5, 0, 0x14000
	v_add_u32_e32 v140, s80, v185
	v_add_u32_e32 v166, s5, v185
	ds_read_b128 v[128:131], v140
	ds_read_b128 v[132:135], v140 offset:1024
	ds_read_b128 v[136:139], v140 offset:2048
	ds_read_b128 v[140:143], v140 offset:3072
	ds_read_b128 v[144:147], v166
	ds_read_b128 v[148:151], v166 offset:1024
	ds_read_b128 v[152:155], v166 offset:2048
	ds_read_b128 v[166:169], v166 offset:3072
	v_lshl_add_u64 v[182:183], s[40:41], 0, v[162:163]
	s_add_i32 m0, s28, 0xc000
	ds_read_b128 v[170:173], v188
	ds_read_b128 v[174:177], v188 offset:1024
	ds_read_b128 v[178:181], v188 offset:2048
	ds_read_b128 v[214:217], v188 offset:3072
	ds_read_b128 v[218:221], v188 offset:4096
	ds_read_b128 v[222:225], v188 offset:5120
	ds_read_b128 v[226:229], v188 offset:6144
	ds_read_b128 v[230:233], v188 offset:7168
	global_load_lds_dwordx4 v[182:183], off
	v_lshl_add_u64 v[182:183], s[40:41], 0, v[164:165]
	s_add_i32 m0, s28, 0xe000
	s_nop 0
	global_load_lds_dwordx4 v[182:183], off
	s_waitcnt vmcnt(24)
	s_waitcnt lgkmcnt(0)
	s_barrier
	s_waitcnt lgkmcnt(0)
	v_mfma_f32_16x16x32_bf16 v[124:127], v[128:131], v[170:173], 0
	v_mfma_f32_16x16x32_bf16 v[120:123], v[136:139], v[170:173], 0
	v_mfma_f32_16x16x32_bf16 v[108:111], v[128:131], v[178:181], 0
	v_mfma_f32_16x16x32_bf16 v[104:107], v[136:139], v[178:181], 0
	v_mfma_f32_16x16x32_bf16 v[92:95], v[128:131], v[218:221], 0
	v_mfma_f32_16x16x32_bf16 v[88:91], v[136:139], v[218:221], 0
	v_mfma_f32_16x16x32_bf16 v[76:79], v[128:131], v[226:229], 0
	v_mfma_f32_16x16x32_bf16 v[72:75], v[136:139], v[226:229], 0
	v_mfma_f32_16x16x32_bf16 v[124:127], v[132:135], v[174:177], v[124:127]
	v_mfma_f32_16x16x32_bf16 v[120:123], v[140:143], v[174:177], v[120:123]
	v_mfma_f32_16x16x32_bf16 v[108:111], v[132:135], v[214:217], v[108:111]
	v_mfma_f32_16x16x32_bf16 v[104:107], v[140:143], v[214:217], v[104:107]
	v_mfma_f32_16x16x32_bf16 v[92:95], v[132:135], v[222:225], v[92:95]
	v_mfma_f32_16x16x32_bf16 v[88:91], v[140:143], v[222:225], v[88:91]
	v_mfma_f32_16x16x32_bf16 v[76:79], v[132:135], v[230:233], v[76:79]
	v_mfma_f32_16x16x32_bf16 v[72:75], v[140:143], v[230:233], v[72:75]
	v_mfma_f32_16x16x32_bf16 v[116:119], v[144:147], v[170:173], 0
	v_mfma_f32_16x16x32_bf16 v[112:115], v[152:155], v[170:173], 0
	v_mfma_f32_16x16x32_bf16 v[100:103], v[144:147], v[178:181], 0
	v_mfma_f32_16x16x32_bf16 v[96:99], v[152:155], v[178:181], 0
	v_mfma_f32_16x16x32_bf16 v[84:87], v[144:147], v[218:221], 0
	v_mfma_f32_16x16x32_bf16 v[80:83], v[152:155], v[218:221], 0
	v_mfma_f32_16x16x32_bf16 v[68:71], v[144:147], v[226:229], 0
	v_mfma_f32_16x16x32_bf16 v[64:67], v[152:155], v[226:229], 0
	v_mfma_f32_16x16x32_bf16 v[116:119], v[148:151], v[174:177], v[116:119]
	v_mfma_f32_16x16x32_bf16 v[112:115], v[166:169], v[174:177], v[112:115]
	v_mfma_f32_16x16x32_bf16 v[100:103], v[148:151], v[214:217], v[100:103]
	v_mfma_f32_16x16x32_bf16 v[96:99], v[166:169], v[214:217], v[96:99]
	v_mfma_f32_16x16x32_bf16 v[84:87], v[148:151], v[222:225], v[84:87]
	v_mfma_f32_16x16x32_bf16 v[80:83], v[166:169], v[222:225], v[80:83]
	v_mfma_f32_16x16x32_bf16 v[68:71], v[148:151], v[230:233], v[68:71]
	v_mfma_f32_16x16x32_bf16 v[64:67], v[166:169], v[230:233], v[64:67]
	s_barrier
	s_add_i32 s80, s80, s27
	v_lshl_add_u64 v[182:183], s[46:47], 0, v[192:193]
	s_mov_b32 m0, s80
	ds_read_b128 v[170:173], v188 offset:16384
	ds_read_b128 v[174:177], v188 offset:17408
	ds_read_b128 v[178:181], v188 offset:18432
	ds_read_b128 v[214:217], v188 offset:19456
	ds_read_b128 v[218:221], v188 offset:20480
	ds_read_b128 v[222:225], v188 offset:21504
	ds_read_b128 v[226:229], v188 offset:22528
	ds_read_b128 v[230:233], v188 offset:23552
	global_load_lds_dwordx4 v[182:183], off
	s_add_i32 m0, s80, 0x2000
	v_lshl_add_u64 v[190:191], s[46:47], 0, v[160:161]
	s_add_u32 s46, s46, s30
	s_addc_u32 s47, s47, 0
	s_add_i32 s5, s5, s27
	global_load_lds_dwordx4 v[190:191], off
	v_lshl_add_u64 v[200:201], s[46:47], 0, v[192:193]
	s_mov_b32 m0, s5
	v_lshl_add_u64 v[234:235], s[46:47], 0, v[160:161]
	global_load_lds_dwordx4 v[200:201], off
	s_add_i32 m0, s5, 0x2000
	v_lshl_add_u64 v[236:237], s[42:43], 0, v[156:157]
	global_load_lds_dwordx4 v[234:235], off
	s_mov_b32 m0, s28
	v_lshl_add_u64 v[238:239], s[42:43], 0, v[158:159]
	global_load_lds_dwordx4 v[236:237], off
	s_mov_b32 m0, s69
	s_nop 0
	global_load_lds_dwordx4 v[238:239], off
	s_waitcnt vmcnt(24)
	s_waitcnt lgkmcnt(0)
	s_barrier
	s_waitcnt lgkmcnt(0)
	v_mfma_f32_16x16x32_bf16 v[60:63], v[128:131], v[170:173], 0
	v_mfma_f32_16x16x32_bf16 v[56:59], v[136:139], v[170:173], 0
	v_mfma_f32_16x16x32_bf16 v[44:47], v[128:131], v[178:181], 0
	v_mfma_f32_16x16x32_bf16 v[40:43], v[136:139], v[178:181], 0
	v_mfma_f32_16x16x32_bf16 v[28:31], v[128:131], v[218:221], 0
	v_mfma_f32_16x16x32_bf16 v[24:27], v[136:139], v[218:221], 0
	v_mfma_f32_16x16x32_bf16 v[12:15], v[128:131], v[226:229], 0
	v_mfma_f32_16x16x32_bf16 v[8:11], v[136:139], v[226:229], 0
	v_mfma_f32_16x16x32_bf16 v[60:63], v[132:135], v[174:177], v[60:63]
	v_mfma_f32_16x16x32_bf16 v[56:59], v[140:143], v[174:177], v[56:59]
	v_mfma_f32_16x16x32_bf16 v[44:47], v[132:135], v[214:217], v[44:47]
	v_mfma_f32_16x16x32_bf16 v[40:43], v[140:143], v[214:217], v[40:43]
	v_mfma_f32_16x16x32_bf16 v[28:31], v[132:135], v[222:225], v[28:31]
	v_mfma_f32_16x16x32_bf16 v[24:27], v[140:143], v[222:225], v[24:27]
	v_mfma_f32_16x16x32_bf16 v[12:15], v[132:135], v[230:233], v[12:15]
	v_mfma_f32_16x16x32_bf16 v[8:11], v[140:143], v[230:233], v[8:11]
	v_mfma_f32_16x16x32_bf16 v[52:55], v[144:147], v[170:173], 0
	v_mfma_f32_16x16x32_bf16 v[48:51], v[152:155], v[170:173], 0
	v_mfma_f32_16x16x32_bf16 v[36:39], v[144:147], v[178:181], 0
	v_mfma_f32_16x16x32_bf16 v[32:35], v[152:155], v[178:181], 0
	v_mfma_f32_16x16x32_bf16 v[20:23], v[144:147], v[218:221], 0
	v_mfma_f32_16x16x32_bf16 v[16:19], v[152:155], v[218:221], 0
	v_mfma_f32_16x16x32_bf16 v[4:7], v[144:147], v[226:229], 0
	v_mfma_f32_16x16x32_bf16 v[0:3], v[152:155], v[226:229], 0
	v_mfma_f32_16x16x32_bf16 v[52:55], v[148:151], v[174:177], v[52:55]
	v_mfma_f32_16x16x32_bf16 v[48:51], v[166:169], v[174:177], v[48:51]
	v_mfma_f32_16x16x32_bf16 v[36:39], v[148:151], v[214:217], v[36:39]
	v_mfma_f32_16x16x32_bf16 v[32:35], v[166:169], v[214:217], v[32:35]
	v_mfma_f32_16x16x32_bf16 v[20:23], v[148:151], v[222:225], v[20:23]
	v_mfma_f32_16x16x32_bf16 v[16:19], v[166:169], v[222:225], v[16:19]
	v_mfma_f32_16x16x32_bf16 v[4:7], v[148:151], v[230:233], v[4:7]
	v_mfma_f32_16x16x32_bf16 v[0:3], v[166:169], v[230:233], v[0:3]
	s_barrier
	s_branch .Lmy_sp3
